# GEMM prologue de-serialisation: all 14 first-tile LDS-DMA pieces issued before the first wait (vmcnt 2 to 8, stagger barrier moved behind the second group) - one exposed memory round trip per gemm cal
# speedup vs baseline: 1.0040x; 1.0040x over previous
; #define PG8_STAGE(bufoff, gbase, voff) do { _Pragma("unroll") for (int _i = 0; _i < 2; ++_i) \
;         __builtin_amdgcn_global_load_lds((const unsigned*)((const char*)(gbase) + (voff)[_i]), (PG8_LAS unsigned*)(lds + (bufoff) + ldsw + _i * 8192), 16, 0, 0); } while (0)
; #define PG8_WAIT_V(n) asm volatile("s_waitcnt vmcnt(" #n ")" ::: "memory")
; #define PG8_BAR __builtin_amdgcn_s_barrier()
; template <class Epi, class Sched, bool ALIGN_EPI = false, bool SP2 = false>
; __device__ __forceinline__ void gemm_phase(PG8_LAS unsigned char* lds, const Gemm g, const Sched& S, const Epi& E) {
;     ...
;     for (int i = 0; i < 2; ++i) { int R, C; stage_rc(tid * 16 + i * 8192, R, C); const int Rb = Epi::PERM ? ((R & ~31) + perm32(R & 31)) : R;
;         voffA[i] = (unsigned)(R * g.ld + C) * 2u; voffB[i] = (unsigned)(Rb * g.ld + C) * 2u; }
;     const size_t kstep = (size_t)(BK * 2);
;     const size_t hstep = (size_t)HALF * g.ld * 2;
;     const size_t tstep = 2 * hstep;
;     const unsigned ldsw = (unsigned)wid * 1024u;
;     const int aoff = lds_byte(wr * 64 + fr, fq * 8), boff = lds_byte(wc * 32 + fr, fq * 8);
;     ...
;     const char* cA = (const char*)g.A + (size_t)cur.pm * tstep + (size_t)cur.ks * K * 2; const char* cB = (const char*)g.Bt + (size_t)cur.pn * tstep + (size_t)cur.ks * K * 2;
;     S.a_ready(cur);
;     if constexpr (SP2) {
;         PG8_STAGE(PG8_SB(0, 0), cB, voffB); PG8_STAGE(PG8_SB(0, 1), cB + hstep, voffB); PG8_STAGE(PG8_SA(0, 0), cA, voffA); PG8_STAGE(PG8_SA(0, 1), cA + hstep, voffA);
;         if (wr == 1) PG8_BAR;
;         PG8_WAIT_V(2); PG8_BAR;
;         PG8_STAGE(PG8_SB(1, 0), cB + kstep, voffB); PG8_STAGE(PG8_SA(1, 0), cA + kstep, voffA); PG8_STAGE(PG8_SB(1, 1), cB + hstep + kstep, voffB);
;         PG8_WAIT_V(6); PG8_BAR;
.LBB0_251:
	s_add_u32 s4, s2, 0xe400000
	s_addc_u32 s5, s3, 0
	s_lshl_b32 s2, s6, 5
	s_add_i32 s36, s10, 0x18000
	s_and_b32 s24, s2, 0x60
	s_add_i32 s65, s36, s12
	s_mov_b64 s[6:7], 0x80
	s_lshl_b32 s23, s11, 13
	s_lshl_b32 s25, s24, 7
	v_lshl_add_u64 v[8:9], v[8:9], 0, s[6:7]
	s_mov_b32 m0, s65
	s_add_i32 s66, s65, 0x2000
	s_add_i32 s67, s61, 0x8000
	s_add_i32 s68, s61, 0xa000
	global_load_lds_dwordx4 v[8:9], off
	v_lshl_add_u64 v[6:7], v[6:7], 0, s[6:7]
	s_mov_b32 m0, s66
	s_add_u32 s2, s42, 0x40080
	global_load_lds_dwordx4 v[6:7], off
	v_lshl_add_u64 v[2:3], v[2:3], 0, s[6:7]
	s_mov_b32 m0, s67
	s_addc_u32 s3, s43, 0
	s_add_i32 s37, s10, 0x1c000
	global_load_lds_dwordx4 v[2:3], off
	v_lshl_add_u64 v[2:3], v[4:5], 0, s[6:7]
	s_mov_b32 m0, s68
	s_add_i32 s69, s37, s12
	global_load_lds_dwordx4 v[2:3], off
	v_lshl_add_u64 v[2:3], s[2:3], 0, v[134:135]
	s_mov_b32 m0, s69
	s_add_i32 s70, s69, 0x2000
	global_load_lds_dwordx4 v[2:3], off
	v_lshl_add_u64 v[2:3], s[2:3], 0, v[130:131]
	s_mov_b32 m0, s70
	s_cmpk_lt_u32 s9, 0x100
	global_load_lds_dwordx4 v[2:3], off
	s_waitcnt vmcnt(8)
	s_barrier
	v_lshrrev_b32_e32 v3, 1, v10
	v_and_b32_e32 v3, 24, v3
	v_and_b32_e32 v2, 15, v10
	v_lshlrev_b32_e32 v4, 1, v3
	v_lshl_or_b32 v150, s11, 6, v2
	v_lshl_or_b32 v2, v2, 6, v4
	v_lshlrev_b32_e32 v4, 2, v10
	v_or_b32_e32 v151, s24, v3
	v_lshlrev_b32_e32 v3, 14, v11
	v_and_b32_e32 v4, 32, v4
	v_and_b32_e32 v3, 0xffff8000, v3
	v_bitop3_b32 v5, v2, s23, v4 bitop3:0xde
	v_bitop3_b32 v2, v2, s25, v4 bitop3:0xde
	v_lshl_add_u32 v3, v12, 11, v3
	v_and_b32_e32 v4, 1, v11
	v_lshl_or_b32 v3, v4, 6, v3
	v_lshl_add_u32 v138, v13, 1, v3
	v_lshlrev_b32_e32 v3, 14, v15
	v_and_b32_e32 v3, 0xffff8000, v3
	s_waitcnt vmcnt(6)
	v_lshl_add_u32 v3, v14, 11, v3
	v_and_b32_e32 v4, 1, v15
	v_lshl_or_b32 v3, v4, 6, v3
	s_sext_i32_i16 s33, s8
	s_cselect_b64 s[8:9], -1, 0
	s_ashr_i32 s71, s27, 31
	v_mov_b32_e32 v139, v135
	v_lshl_add_u32 v140, v16, 1, v3
	v_mov_b32_e32 v141, v135
	s_mov_b32 s72, 0
	v_mov_b64_e32 v[142:143], 0xb58
	v_mov_b64_e32 v[144:145], 0xb57
	v_add_u32_e32 v152, s13, v2
	v_add_u32_e32 v153, s22, v2
	v_add_u32_e32 v154, s10, v5
	v_add_u32_e32 v155, s36, v2
	v_add_u32_e32 v156, s37, v2
	s_movk_i32 s73, 0x1600
	s_barrier
	s_branch .LBB0_254

; #define PG8_STAGE(bufoff, gbase, voff) do { _Pragma("unroll") for (int _i = 0; _i < 2; ++_i) \
;         __builtin_amdgcn_global_load_lds((const unsigned*)((const char*)(gbase) + (voff)[_i]), (PG8_LAS unsigned*)(lds + (bufoff) + ldsw + _i * 8192), 16, 0, 0); } while (0)
; #define PG8_WAIT_V(n) asm volatile("s_waitcnt vmcnt(" #n ")" ::: "memory")
; #define PG8_BAR __builtin_amdgcn_s_barrier()
; template <class Epi, class Sched, bool ALIGN_EPI = false, bool SP2 = false>
; __device__ __forceinline__ void gemm_phase(PG8_LAS unsigned char* lds, const Gemm g, const Sched& S, const Epi& E) {
;     ...
;     for (int i = 0; i < 2; ++i) { int R, C; stage_rc(tid * 16 + i * 8192, R, C); const int Rb = Epi::PERM ? ((R & ~31) + perm32(R & 31)) : R;
;         voffA[i] = (unsigned)(R * g.ld + C) * 2u; voffB[i] = (unsigned)(Rb * g.ld + C) * 2u; }
;     const size_t kstep = (size_t)(BK * 2);
;     const size_t hstep = (size_t)HALF * g.ld * 2;
;     const size_t tstep = 2 * hstep;
;     const unsigned ldsw = (unsigned)wid * 1024u;
;     const int aoff = lds_byte(wr * 64 + fr, fq * 8), boff = lds_byte(wc * 32 + fr, fq * 8);
;     ...
;     const char* cA = (const char*)g.A + (size_t)cur.pm * tstep + (size_t)cur.ks * K * 2; const char* cB = (const char*)g.Bt + (size_t)cur.pn * tstep + (size_t)cur.ks * K * 2;
;     S.a_ready(cur);
;     if constexpr (SP2) {
;         PG8_STAGE(PG8_SB(0, 0), cB, voffB); PG8_STAGE(PG8_SB(0, 1), cB + hstep, voffB); PG8_STAGE(PG8_SA(0, 0), cA, voffA); PG8_STAGE(PG8_SA(0, 1), cA + hstep, voffA);
;         if (wr == 1) PG8_BAR;
;         PG8_WAIT_V(2); PG8_BAR;
;         PG8_STAGE(PG8_SB(1, 0), cB + kstep, voffB); PG8_STAGE(PG8_SA(1, 0), cA + kstep, voffA); PG8_STAGE(PG8_SB(1, 1), cB + hstep + kstep, voffB);
;         PG8_WAIT_V(6); PG8_BAR;
.LBB0_333:
	v_lshrrev_b32_e32 v20, 1, v14
	v_and_b32_e32 v20, 24, v20
	v_and_b32_e32 v19, 15, v14
	v_lshlrev_b32_e32 v21, 1, v20
	v_lshlrev_b32_e32 v14, 2, v14
	s_lshl_b32 s4, s4, 5
	s_lshr_b32 s93, s33, 6
	v_lshl_or_b32 v143, s36, 6, v19
	v_lshl_or_b32 v19, v19, 6, v21
	s_lshl_b32 s33, s36, 13
	v_and_b32_e32 v14, 32, v14
	s_and_b32 s4, s4, 0x60
	v_bitop3_b32 v21, v19, s33, v14 bitop3:0xde
	s_lshl_b32 s33, s4, 7
	v_bitop3_b32 v144, v19, s33, v14 bitop3:0xde
	s_add_i32 s33, s67, s5
	v_lshl_add_u64 v[8:9], v[8:9], 0, s[24:25]
	s_mov_b32 m0, s33
	s_add_i32 s36, s33, 0x2000
	global_load_lds_dwordx4 v[8:9], off
	v_lshl_add_u64 v[6:7], v[6:7], 0, s[24:25]
	s_mov_b32 m0, s36
	s_add_i32 s37, s89, 0x8000
	s_add_i32 s40, s89, 0xa000
	global_load_lds_dwordx4 v[6:7], off
	v_lshl_add_u64 v[2:3], v[2:3], 0, s[24:25]
	s_mov_b32 m0, s37
	s_add_u32 s38, s72, 0xb0080
	global_load_lds_dwordx4 v[2:3], off
	v_lshl_add_u64 v[2:3], v[4:5], 0, s[24:25]
	s_mov_b32 m0, s40
	s_addc_u32 s39, s73, 0
	s_add_i32 s48, s78, s5
	global_load_lds_dwordx4 v[2:3], off
	v_lshl_add_u64 v[2:3], s[38:39], 0, v[130:131]
	s_mov_b32 m0, s48
	s_add_i32 s49, s48, 0x2000
	global_load_lds_dwordx4 v[2:3], off
	v_lshl_add_u64 v[2:3], s[38:39], 0, v[136:137]
	s_mov_b32 m0, s49
	s_add_i32 s50, s93, -2
	global_load_lds_dwordx4 v[2:3], off
	s_waitcnt vmcnt(8)
	s_barrier
	v_cvt_f32_u32_e32 v2, s0
	s_cmpk_lt_u32 s51, 0x100
	s_cselect_b64 s[56:57], -1, 0
	v_or_b32_e32 v145, s4, v20
	v_rcp_iflag_f32_e32 v2, v2
	s_sub_i32 s4, 0, s0
	s_mul_i32 s96, s0, s54
	v_lshrrev_b32_e32 v3, 1, v15
	v_mul_f32_e32 v2, 0x4f7ffffe, v2
	v_cvt_u32_f32_e32 v2, v2
	s_mov_b64 s[38:39], 0xb0080
	s_waitcnt vmcnt(6)
	s_lshr_b32 s51, s84, 1
	v_readfirstlane_b32 s5, v2
	v_cvt_f32_ubyte0_e32 v2, s84
	v_rcp_iflag_f32_e32 v2, v2
	s_mul_i32 s4, s4, s5
	s_mul_hi_u32 s4, s5, s4
	s_add_i32 s54, s5, s4
	v_mul_f32_e32 v2, 0x4f7ffffe, v2
	v_cvt_u32_f32_e32 v2, v2
	s_sub_i32 s4, 0, s84
	s_mov_b32 s97, 0
	v_add_u32_e32 v146, s28, v21
	v_readfirstlane_b32 s5, v2
	s_mul_i32 s4, s4, s5
	s_mul_hi_u32 s4, s5, s4
	v_mul_lo_u32 v2, v16, s82
	s_add_i32 s55, s5, s4
	v_mad_u64_u32 v[2:3], s[4:5], v3, s83, v[2:3]
	v_or_b32_e32 v2, v2, v17
	v_add_lshl_u32 v2, v2, v18, 1
	v_mov_b32_e32 v3, v131
	v_lshl_add_u64 v[138:139], v[2:3], 0, s[38:39]
	v_lshrrev_b32_e32 v3, 1, v10
	v_mul_lo_u32 v2, v11, s82
	v_mad_u64_u32 v[2:3], s[4:5], v3, s83, v[2:3]
	v_or_b32_e32 v2, v2, v12
	v_add_lshl_u32 v2, v2, v13, 1
	v_mov_b32_e32 v3, v131
	v_lshl_add_u64 v[140:141], v[2:3], 0, s[38:39]
	v_add_u32_e32 v147, s65, v144
	v_add_u32_e32 v148, s66, v144
	v_add_u32_e32 v149, s67, v144
	s_barrier
	s_branch .LBB0_336

; #define PG8_STAGE(bufoff, gbase, voff) do { _Pragma("unroll") for (int _i = 0; _i < 2; ++_i) \
;         __builtin_amdgcn_global_load_lds((const unsigned*)((const char*)(gbase) + (voff)[_i]), (PG8_LAS unsigned*)(lds + (bufoff) + ldsw + _i * 8192), 16, 0, 0); } while (0)
; #define PG8_WAIT_V(n) asm volatile("s_waitcnt vmcnt(" #n ")" ::: "memory")
; #define PG8_BAR __builtin_amdgcn_s_barrier()
; template <class Epi, class Sched, bool ALIGN_EPI = false, bool SP2 = false>
; __device__ __forceinline__ void gemm_phase(PG8_LAS unsigned char* lds, const Gemm g, const Sched& S, const Epi& E) {
;     ...
;     for (int i = 0; i < 2; ++i) { int R, C; stage_rc(tid * 16 + i * 8192, R, C); const int Rb = Epi::PERM ? ((R & ~31) + perm32(R & 31)) : R;
;         voffA[i] = (unsigned)(R * g.ld + C) * 2u; voffB[i] = (unsigned)(Rb * g.ld + C) * 2u; }
;     const size_t kstep = (size_t)(BK * 2);
;     const size_t hstep = (size_t)HALF * g.ld * 2;
;     const size_t tstep = 2 * hstep;
;     const unsigned ldsw = (unsigned)wid * 1024u;
;     const int aoff = lds_byte(wr * 64 + fr, fq * 8), boff = lds_byte(wc * 32 + fr, fq * 8);
;     ...
;     const char* cA = (const char*)g.A + (size_t)cur.pm * tstep + (size_t)cur.ks * K * 2; const char* cB = (const char*)g.Bt + (size_t)cur.pn * tstep + (size_t)cur.ks * K * 2;
;     S.a_ready(cur);
;     if constexpr (SP2) {
;         PG8_STAGE(PG8_SB(0, 0), cB, voffB); PG8_STAGE(PG8_SB(0, 1), cB + hstep, voffB); PG8_STAGE(PG8_SA(0, 0), cA, voffA); PG8_STAGE(PG8_SA(0, 1), cA + hstep, voffA);
;         if (wr == 1) PG8_BAR;
;         PG8_WAIT_V(2); PG8_BAR;
;         PG8_STAGE(PG8_SB(1, 0), cB + kstep, voffB); PG8_STAGE(PG8_SA(1, 0), cA + kstep, voffA); PG8_STAGE(PG8_SB(1, 1), cB + hstep + kstep, voffB);
;         PG8_WAIT_V(6); PG8_BAR;
.LBB0_511:
	s_add_u32 s4, s2, 0xe400000
	s_addc_u32 s5, s3, 0
	s_add_u32 s6, s2, 0x12600000
	s_addc_u32 s7, s3, 0
	s_lshl_b32 s2, s8, 5
	s_add_i32 s37, s12, 0x18000
	s_and_b32 s33, s2, 0x60
	s_add_i32 s70, s37, s22
	s_mov_b64 s[8:9], 0x80
	s_lshl_b32 s25, s13, 13
	s_lshl_b32 s36, s33, 7
	v_lshl_add_u64 v[8:9], v[8:9], 0, s[8:9]
	s_mov_b32 m0, s70
	s_add_i32 s71, s70, 0x2000
	s_add_i32 s72, s66, 0x8000
	s_add_i32 s73, s66, 0xa000
	global_load_lds_dwordx4 v[8:9], off
	v_lshl_add_u64 v[4:5], v[4:5], 0, s[8:9]
	s_mov_b32 m0, s71
	s_add_u32 s2, s46, 0x40080
	global_load_lds_dwordx4 v[4:5], off
	v_lshl_add_u64 v[2:3], v[2:3], 0, s[8:9]
	s_mov_b32 m0, s72
	s_addc_u32 s3, s47, 0
	s_add_i32 s38, s12, 0x1c000
	global_load_lds_dwordx4 v[2:3], off
	v_lshl_add_u64 v[2:3], v[6:7], 0, s[8:9]
	s_mov_b32 m0, s73
	s_add_i32 s74, s38, s22
	global_load_lds_dwordx4 v[2:3], off
	v_lshl_add_u64 v[2:3], s[2:3], 0, v[134:135]
	s_mov_b32 m0, s74
	s_add_i32 s75, s74, 0x2000
	global_load_lds_dwordx4 v[2:3], off
	v_lshl_add_u64 v[2:3], s[2:3], 0, v[130:131]
	s_mov_b32 m0, s75
	s_cmpk_lt_u32 s11, 0x100
	global_load_lds_dwordx4 v[2:3], off
	s_waitcnt vmcnt(8)
	s_barrier
	v_lshrrev_b32_e32 v3, 1, v10
	v_and_b32_e32 v3, 24, v3
	v_and_b32_e32 v2, 15, v10
	v_lshlrev_b32_e32 v4, 1, v3
	v_lshl_or_b32 v158, s13, 6, v2
	v_lshl_or_b32 v2, v2, 6, v4
	v_lshlrev_b32_e32 v4, 2, v10
	v_or_b32_e32 v159, s33, v3
	v_lshlrev_b32_e32 v3, 14, v11
	v_and_b32_e32 v4, 32, v4
	v_and_b32_e32 v3, 0xffff8000, v3
	v_bitop3_b32 v5, v2, s25, v4 bitop3:0xde
	v_bitop3_b32 v2, v2, s36, v4 bitop3:0xde
	v_lshl_add_u32 v3, v12, 11, v3
	v_and_b32_e32 v4, 1, v11
	v_lshl_or_b32 v3, v4, 6, v3
	v_lshl_add_u32 v140, v13, 1, v3
	v_lshlrev_b32_e32 v3, 14, v15
	v_and_b32_e32 v3, 0xffff8000, v3
	s_waitcnt vmcnt(6)
	v_lshl_add_u32 v3, v14, 11, v3
	v_and_b32_e32 v4, 1, v15
	v_lshl_or_b32 v3, v4, 6, v3
	s_sext_i32_i8 s84, s10
	v_or_b32_e32 v160, 0xfffffe00, v159
	s_cselect_b64 s[10:11], -1, 0
	s_ashr_i32 s76, s26, 31
	v_mov_b32_e32 v141, v139
	v_lshl_add_u32 v142, v16, 1, v3
	v_mov_b32_e32 v143, v139
	s_mov_b32 s77, 0
	v_mov_b64_e32 v[144:145], 0x420
	v_mov_b64_e32 v[146:147], 0x41f
	v_add_u32_e32 v161, s23, v2
	v_add_u32_e32 v162, s24, v2
	v_add_u32_e32 v163, s12, v5
	v_add_u32_e32 v164, s37, v2
	v_add_u32_e32 v165, s38, v2
	s_mov_b32 s78, 0x24000
	s_mov_b32 s79, 0x28000
	s_mov_b32 s80, 0x40000
	s_mov_b64 s[12:13], 0x48000
	s_mov_b32 s81, 0x48000
	s_mov_b64 s[22:23], 0x50000
	s_mov_b32 s82, 0x50000
	s_mov_b64 s[24:25], 0x58000
	s_mov_b32 s83, 0x58000
	s_barrier
	s_branch .LBB0_514

; #define PG8_STAGE(bufoff, gbase, voff) do { _Pragma("unroll") for (int _i = 0; _i < 2; ++_i) \
;         __builtin_amdgcn_global_load_lds((const unsigned*)((const char*)(gbase) + (voff)[_i]), (PG8_LAS unsigned*)(lds + (bufoff) + ldsw + _i * 8192), 16, 0, 0); } while (0)
; #define PG8_WAIT_V(n) asm volatile("s_waitcnt vmcnt(" #n ")" ::: "memory")
; #define PG8_BAR __builtin_amdgcn_s_barrier()
; template <class Epi, class Sched, bool ALIGN_EPI = false, bool SP2 = false>
; __device__ __forceinline__ void gemm_phase(PG8_LAS unsigned char* lds, const Gemm g, const Sched& S, const Epi& E) {
;     ...
;     for (int i = 0; i < 2; ++i) { int R, C; stage_rc(tid * 16 + i * 8192, R, C); const int Rb = Epi::PERM ? ((R & ~31) + perm32(R & 31)) : R;
;         voffA[i] = (unsigned)(R * g.ld + C) * 2u; voffB[i] = (unsigned)(Rb * g.ld + C) * 2u; }
;     const size_t kstep = (size_t)(BK * 2);
;     const size_t hstep = (size_t)HALF * g.ld * 2;
;     const size_t tstep = 2 * hstep;
;     const unsigned ldsw = (unsigned)wid * 1024u;
;     const int aoff = lds_byte(wr * 64 + fr, fq * 8), boff = lds_byte(wc * 32 + fr, fq * 8);
;     ...
;     const char* cA = (const char*)g.A + (size_t)cur.pm * tstep + (size_t)cur.ks * K * 2; const char* cB = (const char*)g.Bt + (size_t)cur.pn * tstep + (size_t)cur.ks * K * 2;
;     S.a_ready(cur);
;     if constexpr (SP2) {
;         PG8_STAGE(PG8_SB(0, 0), cB, voffB); PG8_STAGE(PG8_SB(0, 1), cB + hstep, voffB); PG8_STAGE(PG8_SA(0, 0), cA, voffA); PG8_STAGE(PG8_SA(0, 1), cA + hstep, voffA);
;         if (wr == 1) PG8_BAR;
;         PG8_WAIT_V(2); PG8_BAR;
;         PG8_STAGE(PG8_SB(1, 0), cB + kstep, voffB); PG8_STAGE(PG8_SA(1, 0), cA + kstep, voffA); PG8_STAGE(PG8_SB(1, 1), cB + hstep + kstep, voffB);
;         PG8_WAIT_V(6); PG8_BAR;
.LBB0_690:
	s_add_i32 s88, s65, s3
	v_lshl_add_u64 v[10:11], v[10:11], 0, s[18:19]
	s_mov_b32 m0, s88
	s_add_i32 s89, s88, 0x2000
	global_load_lds_dwordx4 v[10:11], off
	v_lshl_add_u64 v[6:7], v[6:7], 0, s[18:19]
	s_mov_b32 m0, s89
	s_add_i32 s90, s83, 0x8000
	global_load_lds_dwordx4 v[6:7], off
	v_lshl_add_u64 v[6:7], v[8:9], 0, s[18:19]
	s_mov_b32 m0, s90
	s_add_i32 s91, s83, 0xa000
	global_load_lds_dwordx4 v[6:7], off
	v_lshl_add_u64 v[6:7], v[12:13], 0, s[18:19]
	s_mov_b32 m0, s91
	s_add_i32 s92, s66, s3
	global_load_lds_dwordx4 v[6:7], off
	v_lshl_add_u64 v[4:5], v[4:5], 0, s[18:19]
	s_mov_b32 m0, s92
	s_add_i32 s93, s92, 0x2000
	global_load_lds_dwordx4 v[4:5], off
	v_lshl_add_u64 v[2:3], v[2:3], 0, s[18:19]
	s_mov_b32 m0, s93
	v_lshrrev_b32_e32 v22, 1, v17
	global_load_lds_dwordx4 v[2:3], off
	s_waitcnt vmcnt(8)
	s_barrier
	v_cvt_f32_ubyte0_e32 v2, s44
	v_rcp_iflag_f32_e32 v2, v2
	v_and_b32_e32 v22, 24, v22
	v_and_b32_e32 v21, 15, v17
	v_lshlrev_b32_e32 v23, 1, v22
	v_mul_f32_e32 v2, 0x4f7ffffe, v2
	v_cvt_u32_f32_e32 v2, v2
	v_lshlrev_b32_e32 v17, 2, v17
	s_lshl_b32 s2, s2, 5
	s_lshr_b32 s87, s45, 6
	v_readfirstlane_b32 s3, v2
	v_cvt_f32_ubyte0_e32 v2, s37
	v_rcp_iflag_f32_e32 v2, v2
	v_lshl_or_b32 v145, s50, 6, v21
	v_lshl_or_b32 v21, v21, 6, v23
	s_lshl_b32 s30, s50, 13
	v_and_b32_e32 v17, 32, v17
	s_and_b32 s2, s2, 0x60
	v_bitop3_b32 v23, v21, s30, v17 bitop3:0xde
	s_lshl_b32 s30, s2, 7
	s_add_i32 s95, s87, -2
	v_mul_f32_e32 v2, 0x4f7ffffe, v2
	s_cmpk_lt_u32 s33, 0x100
	v_cvt_u32_f32_e32 v2, v2
	s_cselect_b64 s[52:53], -1, 0
	v_or_b32_e32 v147, s2, v22
	s_sub_i32 s2, 0, s44
	s_mul_i32 s2, s2, s3
	s_mul_hi_u32 s2, s3, s2
	s_add_i32 s48, s3, s2
	v_readfirstlane_b32 s3, v2
	v_add_u32_e32 v2, v20, v18
	s_sub_i32 s2, 0, s37
	v_add_lshl_u32 v2, v2, v19, 1
	v_mov_b32_e32 v3, v131
	s_waitcnt vmcnt(6)
	s_mul_i32 s2, s2, s3
	v_lshl_add_u64 v[138:139], s[0:1], 0, v[2:3]
	v_add_u32_e32 v2, v16, v14
	v_bitop3_b32 v146, v21, s30, v17 bitop3:0xde
	s_mul_hi_u32 s2, s3, s2
	v_add_lshl_u32 v2, v2, v15, 1
	s_sext_i32_i8 s51, s49
	s_mul_i32 s96, s44, s23
	s_mov_b32 s45, s1
	s_mov_b32 s23, s22
	s_mov_b32 s56, s22
	s_mov_b32 s57, s22
	s_mov_b32 s33, 0
	s_add_i32 s49, s3, s2
	v_lshl_add_u64 v[140:141], s[0:1], 0, v[2:3]
	v_add_u32_e32 v148, s28, v23
	v_add_u32_e32 v149, s63, v146
	v_add_u32_e32 v150, s64, v146
	v_add_u32_e32 v151, s65, v146
	s_barrier
	s_branch .LBB0_693

; #define PG8_STAGE(bufoff, gbase, voff) do { _Pragma("unroll") for (int _i = 0; _i < 2; ++_i) \
;         __builtin_amdgcn_global_load_lds((const unsigned*)((const char*)(gbase) + (voff)[_i]), (PG8_LAS unsigned*)(lds + (bufoff) + ldsw + _i * 8192), 16, 0, 0); } while (0)
; #define PG8_WAIT_V(n) asm volatile("s_waitcnt vmcnt(" #n ")" ::: "memory")
; #define PG8_BAR __builtin_amdgcn_s_barrier()
; template <class Epi, class Sched, bool ALIGN_EPI = false, bool SP2 = false>
; __device__ __forceinline__ void gemm_phase(PG8_LAS unsigned char* lds, const Gemm g, const Sched& S, const Epi& E) {
;     ...
;     for (int i = 0; i < 2; ++i) { int R, C; stage_rc(tid * 16 + i * 8192, R, C); const int Rb = Epi::PERM ? ((R & ~31) + perm32(R & 31)) : R;
;         voffA[i] = (unsigned)(R * g.ld + C) * 2u; voffB[i] = (unsigned)(Rb * g.ld + C) * 2u; }
;     const size_t kstep = (size_t)(BK * 2);
;     const size_t hstep = (size_t)HALF * g.ld * 2;
;     const size_t tstep = 2 * hstep;
;     const unsigned ldsw = (unsigned)wid * 1024u;
;     const int aoff = lds_byte(wr * 64 + fr, fq * 8), boff = lds_byte(wc * 32 + fr, fq * 8);
;     ...
;     const char* cA = (const char*)g.A + (size_t)cur.pm * tstep + (size_t)cur.ks * K * 2; const char* cB = (const char*)g.Bt + (size_t)cur.pn * tstep + (size_t)cur.ks * K * 2;
;     S.a_ready(cur);
;     if constexpr (SP2) {
;         PG8_STAGE(PG8_SB(0, 0), cB, voffB); PG8_STAGE(PG8_SB(0, 1), cB + hstep, voffB); PG8_STAGE(PG8_SA(0, 0), cA, voffA); PG8_STAGE(PG8_SA(0, 1), cA + hstep, voffA);
;         if (wr == 1) PG8_BAR;
;         PG8_WAIT_V(2); PG8_BAR;
;         PG8_STAGE(PG8_SB(1, 0), cB + kstep, voffB); PG8_STAGE(PG8_SA(1, 0), cA + kstep, voffA); PG8_STAGE(PG8_SB(1, 1), cB + hstep + kstep, voffB);
;         PG8_WAIT_V(6); PG8_BAR;
.LBB0_846:
	s_lshl_b32 s4, s4, 5
	s_add_i32 s48, s67, s43
	s_and_b32 s4, s4, 0x60
	v_lshl_add_u64 v[8:9], v[8:9], 0, s[16:17]
	s_mov_b32 m0, s48
	s_add_i32 s49, s48, 0x2000
	s_lshr_b32 s81, s41, 6
	s_lshl_b32 s41, s5, 13
	s_lshl_b32 s46, s4, 7
	global_load_lds_dwordx4 v[8:9], off
	v_lshl_add_u64 v[6:7], v[6:7], 0, s[16:17]
	s_mov_b32 m0, s49
	s_add_i32 s50, s77, 0x8000
	s_add_i32 s51, s77, 0xa000
	global_load_lds_dwordx4 v[6:7], off
	v_lshl_add_u64 v[2:3], v[2:3], 0, s[16:17]
	s_mov_b32 m0, s50
	s_add_u32 s44, s56, 0x40080
	global_load_lds_dwordx4 v[2:3], off
	v_lshl_add_u64 v[2:3], v[4:5], 0, s[16:17]
	s_mov_b32 m0, s51
	s_addc_u32 s45, s57, 0
	s_add_i32 s82, s70, s43
	global_load_lds_dwordx4 v[2:3], off
	v_lshl_add_u64 v[2:3], s[44:45], 0, v[130:131]
	s_mov_b32 m0, s82
	s_add_i32 s83, s82, 0x2000
	global_load_lds_dwordx4 v[2:3], off
	v_lshl_add_u64 v[2:3], s[44:45], 0, v[136:137]
	s_mov_b32 m0, s83
	s_add_i32 s84, s81, -2
	global_load_lds_dwordx4 v[2:3], off
	s_waitcnt vmcnt(8)
	s_barrier
	v_lshrrev_b32_e32 v3, 1, v10
	v_and_b32_e32 v3, 24, v3
	v_and_b32_e32 v2, 15, v10
	v_lshlrev_b32_e32 v4, 1, v3
	v_lshl_or_b32 v143, s5, 6, v2
	v_lshl_or_b32 v2, v2, 6, v4
	v_lshlrev_b32_e32 v4, 2, v10
	v_and_b32_e32 v4, 32, v4
	v_bitop3_b32 v5, v2, s41, v4 bitop3:0xde
	v_bitop3_b32 v2, v2, s46, v4 bitop3:0xde
	v_cvt_f32_u32_e32 v4, s0
	v_or_b32_e32 v144, s4, v3
	s_cmpk_lt_u32 s40, 0x100
	s_cselect_b64 s[40:41], -1, 0
	v_rcp_iflag_f32_e32 v4, v4
	s_sub_i32 s4, 0, s0
	s_waitcnt vmcnt(6)
	s_lshr_b32 s85, s74, 1
	v_mul_f32_e32 v3, 0x4f7ffffe, v4
	v_cvt_f32_ubyte0_e32 v4, s74
	v_cvt_u32_f32_e32 v3, v3
	v_rcp_iflag_f32_e32 v4, v4
	s_mul_i32 s86, s0, s42
	s_mov_b32 s87, 0
	v_readfirstlane_b32 s5, v3
	v_mul_f32_e32 v3, 0x4f7ffffe, v4
	v_cvt_u32_f32_e32 v3, v3
	s_mul_i32 s4, s4, s5
	s_mul_hi_u32 s4, s5, s4
	s_add_i32 s54, s5, s4
	v_readfirstlane_b32 s5, v3
	v_lshlrev_b32_e32 v3, 14, v14
	v_and_b32_e32 v3, 0xffff8000, v3
	v_lshl_add_u32 v3, v15, 11, v3
	v_and_b32_e32 v4, 1, v14
	v_lshl_or_b32 v3, v4, 6, v3
	v_lshl_add_u32 v138, v16, 1, v3
	v_lshlrev_b32_e32 v3, 14, v11
	s_sub_i32 s4, 0, s74
	v_and_b32_e32 v3, 0xffff8000, v3
	s_mul_i32 s4, s4, s5
	v_lshl_add_u32 v3, v12, 11, v3
	v_and_b32_e32 v4, 1, v11
	s_mul_hi_u32 s4, s5, s4
	v_lshl_or_b32 v3, v4, 6, v3
	s_add_i32 s55, s5, s4
	v_mov_b32_e32 v139, v131
	v_lshl_add_u32 v140, v13, 1, v3
	v_mov_b32_e32 v141, v131
	v_add_u32_e32 v145, s28, v5
	v_add_u32_e32 v146, s65, v2
	v_add_u32_e32 v147, s66, v2
	v_add_u32_e32 v148, s67, v2
	v_add_u32_e32 v149, s70, v2
	s_barrier
	s_branch .LBB0_849

; #define PG8_STAGE(bufoff, gbase, voff) do { _Pragma("unroll") for (int _i = 0; _i < 2; ++_i) \
;         __builtin_amdgcn_global_load_lds((const unsigned*)((const char*)(gbase) + (voff)[_i]), (PG8_LAS unsigned*)(lds + (bufoff) + ldsw + _i * 8192), 16, 0, 0); } while (0)
; #define PG8_WAIT_V(n) asm volatile("s_waitcnt vmcnt(" #n ")" ::: "memory")
; #define PG8_BAR __builtin_amdgcn_s_barrier()
; template <class Epi, class Sched, bool ALIGN_EPI = false, bool SP2 = false>
; __device__ __forceinline__ void gemm_phase(PG8_LAS unsigned char* lds, const Gemm g, const Sched& S, const Epi& E) {
;     ...
;     for (int i = 0; i < 2; ++i) { int R, C; stage_rc(tid * 16 + i * 8192, R, C); const int Rb = Epi::PERM ? ((R & ~31) + perm32(R & 31)) : R;
;         voffA[i] = (unsigned)(R * g.ld + C) * 2u; voffB[i] = (unsigned)(Rb * g.ld + C) * 2u; }
;     const size_t kstep = (size_t)(BK * 2);
;     const size_t hstep = (size_t)HALF * g.ld * 2;
;     const size_t tstep = 2 * hstep;
;     const unsigned ldsw = (unsigned)wid * 1024u;
;     const int aoff = lds_byte(wr * 64 + fr, fq * 8), boff = lds_byte(wc * 32 + fr, fq * 8);
;     ...
;     const char* cA = (const char*)g.A + (size_t)cur.pm * tstep + (size_t)cur.ks * K * 2; const char* cB = (const char*)g.Bt + (size_t)cur.pn * tstep + (size_t)cur.ks * K * 2;
;     S.a_ready(cur);
;     if constexpr (SP2) {
;         PG8_STAGE(PG8_SB(0, 0), cB, voffB); PG8_STAGE(PG8_SB(0, 1), cB + hstep, voffB); PG8_STAGE(PG8_SA(0, 0), cA, voffA); PG8_STAGE(PG8_SA(0, 1), cA + hstep, voffA);
;         if (wr == 1) PG8_BAR;
;         PG8_WAIT_V(2); PG8_BAR;
;         PG8_STAGE(PG8_SB(1, 0), cB + kstep, voffB); PG8_STAGE(PG8_SA(1, 0), cA + kstep, voffA); PG8_STAGE(PG8_SB(1, 1), cB + hstep + kstep, voffB);
;         PG8_WAIT_V(6); PG8_BAR;
.LBB0_1032:
	s_add_u32 s4, s2, 0xe400000
	s_addc_u32 s5, s3, 0
	s_lshl_b32 s2, s6, 5
	s_add_i32 s24, s10, 0x18000
	s_and_b32 s16, s2, 0x60
	s_add_i32 s45, s24, s12
	s_mov_b64 s[6:7], 0x80
	s_lshl_b32 s15, s11, 13
	s_lshl_b32 s17, s16, 7
	v_lshl_add_u64 v[8:9], v[8:9], 0, s[6:7]
	s_mov_b32 m0, s45
	s_add_i32 s46, s45, 0x2000
	s_add_i32 s47, s41, 0x8000
	s_add_i32 s52, s41, 0xa000
	global_load_lds_dwordx4 v[8:9], off
	v_lshl_add_u64 v[6:7], v[6:7], 0, s[6:7]
	s_mov_b32 m0, s46
	s_add_u32 s2, s20, 0x40080
	global_load_lds_dwordx4 v[6:7], off
	v_lshl_add_u64 v[2:3], v[2:3], 0, s[6:7]
	s_mov_b32 m0, s47
	s_addc_u32 s3, s21, 0
	s_add_i32 s25, s10, 0x1c000
	global_load_lds_dwordx4 v[2:3], off
	v_lshl_add_u64 v[2:3], v[4:5], 0, s[6:7]
	s_mov_b32 m0, s52
	s_add_i32 s53, s25, s12
	global_load_lds_dwordx4 v[2:3], off
	v_lshl_add_u64 v[2:3], s[2:3], 0, v[134:135]
	s_mov_b32 m0, s53
	s_add_i32 s56, s53, 0x2000
	global_load_lds_dwordx4 v[2:3], off
	v_lshl_add_u64 v[2:3], s[2:3], 0, v[130:131]
	s_mov_b32 m0, s56
	s_cmpk_lt_u32 s9, 0x100
	global_load_lds_dwordx4 v[2:3], off
	s_waitcnt vmcnt(8)
	s_barrier
	v_lshrrev_b32_e32 v3, 1, v10
	v_and_b32_e32 v3, 24, v3
	v_and_b32_e32 v2, 15, v10
	v_lshlrev_b32_e32 v4, 1, v3
	v_lshl_or_b32 v150, s11, 6, v2
	v_lshl_or_b32 v2, v2, 6, v4
	v_lshlrev_b32_e32 v4, 2, v10
	v_or_b32_e32 v151, s16, v3
	v_lshlrev_b32_e32 v3, 14, v11
	v_and_b32_e32 v4, 32, v4
	v_and_b32_e32 v3, 0xffff8000, v3
	v_bitop3_b32 v5, v2, s15, v4 bitop3:0xde
	v_bitop3_b32 v2, v2, s17, v4 bitop3:0xde
	v_lshl_add_u32 v3, v12, 11, v3
	v_and_b32_e32 v4, 1, v11
	v_lshl_or_b32 v3, v4, 6, v3
	v_lshl_add_u32 v138, v13, 1, v3
	v_lshlrev_b32_e32 v3, 14, v15
	v_and_b32_e32 v3, 0xffff8000, v3
	s_waitcnt vmcnt(6)
	v_lshl_add_u32 v3, v14, 11, v3
	v_and_b32_e32 v4, 1, v15
	v_lshl_or_b32 v3, v4, 6, v3
	s_sext_i32_i16 s33, s8
	s_cselect_b64 s[8:9], -1, 0
	s_ashr_i32 s57, s26, 31
	v_mov_b32_e32 v139, v135
	v_lshl_add_u32 v140, v16, 1, v3
	v_mov_b32_e32 v141, v135
	s_mov_b32 s60, 0
	v_mov_b64_e32 v[142:143], 0xb58
	v_mov_b64_e32 v[144:145], 0xb57
	v_add_u32_e32 v152, s13, v2
	v_add_u32_e32 v153, s14, v2
	v_add_u32_e32 v154, s10, v5
	v_add_u32_e32 v155, s24, v2
	v_add_u32_e32 v156, s25, v2
	s_movk_i32 s61, 0x1600
	s_barrier
	s_branch .LBB0_1035

; #define PG8_STAGE(bufoff, gbase, voff) do { _Pragma("unroll") for (int _i = 0; _i < 2; ++_i) \
;         __builtin_amdgcn_global_load_lds((const unsigned*)((const char*)(gbase) + (voff)[_i]), (PG8_LAS unsigned*)(lds + (bufoff) + ldsw + _i * 8192), 16, 0, 0); } while (0)
; #define PG8_WAIT_V(n) asm volatile("s_waitcnt vmcnt(" #n ")" ::: "memory")
; #define PG8_BAR __builtin_amdgcn_s_barrier()
; template <class Epi, class Sched, bool ALIGN_EPI = false, bool SP2 = false>
; __device__ __forceinline__ void gemm_phase(PG8_LAS unsigned char* lds, const Gemm g, const Sched& S, const Epi& E) {
;     ...
;     for (int i = 0; i < 2; ++i) { int R, C; stage_rc(tid * 16 + i * 8192, R, C); const int Rb = Epi::PERM ? ((R & ~31) + perm32(R & 31)) : R;
;         voffA[i] = (unsigned)(R * g.ld + C) * 2u; voffB[i] = (unsigned)(Rb * g.ld + C) * 2u; }
;     const size_t kstep = (size_t)(BK * 2);
;     const size_t hstep = (size_t)HALF * g.ld * 2;
;     const size_t tstep = 2 * hstep;
;     const unsigned ldsw = (unsigned)wid * 1024u;
;     const int aoff = lds_byte(wr * 64 + fr, fq * 8), boff = lds_byte(wc * 32 + fr, fq * 8);
;     ...
;     const char* cA = (const char*)g.A + (size_t)cur.pm * tstep + (size_t)cur.ks * K * 2; const char* cB = (const char*)g.Bt + (size_t)cur.pn * tstep + (size_t)cur.ks * K * 2;
;     S.a_ready(cur);
;     if constexpr (SP2) {
;         PG8_STAGE(PG8_SB(0, 0), cB, voffB); PG8_STAGE(PG8_SB(0, 1), cB + hstep, voffB); PG8_STAGE(PG8_SA(0, 0), cA, voffA); PG8_STAGE(PG8_SA(0, 1), cA + hstep, voffA);
;         if (wr == 1) PG8_BAR;
;         PG8_WAIT_V(2); PG8_BAR;
;         PG8_STAGE(PG8_SB(1, 0), cB + kstep, voffB); PG8_STAGE(PG8_SA(1, 0), cA + kstep, voffA); PG8_STAGE(PG8_SB(1, 1), cB + hstep + kstep, voffB);
;         PG8_WAIT_V(6); PG8_BAR;
.LBB0_1113:
	s_lshl_b32 s4, s4, 5
	s_add_i32 s48, s65, s38
	s_and_b32 s4, s4, 0x60
	v_lshl_add_u64 v[8:9], v[8:9], 0, s[16:17]
	s_mov_b32 m0, s48
	s_add_i32 s49, s48, 0x2000
	s_lshr_b32 s81, s42, 6
	s_lshl_b32 s39, s5, 13
	s_lshl_b32 s52, s4, 7
	global_load_lds_dwordx4 v[8:9], off
	v_lshl_add_u64 v[6:7], v[6:7], 0, s[16:17]
	s_mov_b32 m0, s49
	s_add_i32 s50, s77, 0x8000
	s_add_i32 s51, s77, 0xa000
	global_load_lds_dwordx4 v[6:7], off
	v_lshl_add_u64 v[2:3], v[2:3], 0, s[16:17]
	s_mov_b32 m0, s50
	s_add_u32 s42, s46, 0xb0080
	global_load_lds_dwordx4 v[2:3], off
	v_lshl_add_u64 v[2:3], v[4:5], 0, s[16:17]
	s_mov_b32 m0, s51
	s_addc_u32 s43, s47, 0
	s_add_i32 s83, s66, s38
	global_load_lds_dwordx4 v[2:3], off
	v_lshl_add_u64 v[2:3], s[42:43], 0, v[130:131]
	s_mov_b32 m0, s83
	s_add_i32 s84, s83, 0x2000
	global_load_lds_dwordx4 v[2:3], off
	v_lshl_add_u64 v[2:3], s[42:43], 0, v[136:137]
	s_mov_b32 m0, s84
	s_add_i32 s86, s81, -2
	global_load_lds_dwordx4 v[2:3], off
	s_waitcnt vmcnt(8)
	s_barrier
	v_lshrrev_b32_e32 v3, 1, v10
	v_and_b32_e32 v3, 24, v3
	v_and_b32_e32 v2, 15, v10
	v_lshlrev_b32_e32 v4, 1, v3
	v_lshl_or_b32 v143, s5, 6, v2
	v_lshl_or_b32 v2, v2, 6, v4
	v_lshlrev_b32_e32 v4, 2, v10
	v_and_b32_e32 v4, 32, v4
	v_bitop3_b32 v5, v2, s39, v4 bitop3:0xde
	v_bitop3_b32 v144, v2, s52, v4 bitop3:0xde
	v_cvt_f32_u32_e32 v2, s0
	v_or_b32_e32 v145, s4, v3
	v_cvt_f32_ubyte0_e32 v3, s72
	v_rcp_iflag_f32_e32 v3, v3
	v_rcp_iflag_f32_e32 v2, v2
	s_cmpk_lt_u32 s41, 0x100
	s_cselect_b64 s[38:39], -1, 0
	s_sub_i32 s4, 0, s0
	v_mul_f32_e32 v2, 0x4f7ffffe, v2
	v_cvt_u32_f32_e32 v2, v2
	s_waitcnt vmcnt(6)
	s_lshr_b32 s87, s72, 1
	s_mul_i32 s88, s0, s40
	v_readfirstlane_b32 s5, v2
	v_mul_f32_e32 v2, 0x4f7ffffe, v3
	v_cvt_u32_f32_e32 v2, v2
	s_mul_i32 s4, s4, s5
	s_mul_hi_u32 s4, s5, s4
	s_add_i32 s54, s5, s4
	s_sub_i32 s4, 0, s72
	v_readfirstlane_b32 s5, v2
	s_mul_i32 s4, s4, s5
	s_mul_hi_u32 s4, s5, s4
	v_lshrrev_b32_e32 v3, 1, v15
	v_mul_lo_u32 v2, v16, s70
	s_add_i32 s55, s5, s4
	v_mad_u64_u32 v[2:3], s[4:5], v3, s71, v[2:3]
	v_or_b32_e32 v2, v2, v17
	v_add_lshl_u32 v2, v2, v18, 1
	v_mov_b32_e32 v3, v131
	v_lshl_add_u64 v[138:139], v[2:3], 0, s[18:19]
	v_lshrrev_b32_e32 v3, 1, v11
	v_mul_lo_u32 v2, v12, s70
	v_mad_u64_u32 v[2:3], s[4:5], v3, s71, v[2:3]
	v_or_b32_e32 v2, v2, v13
	v_add_lshl_u32 v2, v2, v14, 1
	v_mov_b32_e32 v3, v131
	s_mov_b32 s89, 0
	v_lshl_add_u64 v[140:141], v[2:3], 0, s[18:19]
	v_add_u32_e32 v146, s28, v5
	v_add_u32_e32 v147, s63, v144
	v_add_u32_e32 v148, s64, v144
	v_add_u32_e32 v149, s65, v144
	s_barrier
	s_branch .LBB0_1116

; #define PG8_STAGE(bufoff, gbase, voff) do { _Pragma("unroll") for (int _i = 0; _i < 2; ++_i) \
;         __builtin_amdgcn_global_load_lds((const unsigned*)((const char*)(gbase) + (voff)[_i]), (PG8_LAS unsigned*)(lds + (bufoff) + ldsw + _i * 8192), 16, 0, 0); } while (0)
; #define PG8_WAIT_V(n) asm volatile("s_waitcnt vmcnt(" #n ")" ::: "memory")
; #define PG8_BAR __builtin_amdgcn_s_barrier()
; template <class Epi, class Sched, bool ALIGN_EPI = false, bool SP2 = false>
; __device__ __forceinline__ void gemm_phase(PG8_LAS unsigned char* lds, const Gemm g, const Sched& S, const Epi& E) {
;     ...
;     if constexpr (SP2) {
;         PG8_STAGE(PG8_SB(0, 0), cB, voffB); PG8_STAGE(PG8_SB(0, 1), cB + hstep, voffB); PG8_STAGE(PG8_SA(0, 0), cA, voffA); PG8_STAGE(PG8_SA(0, 1), cA + hstep, voffA);
;         if (wr == 1) PG8_BAR;
;         PG8_WAIT_V(2); PG8_BAR;
;         PG8_STAGE(PG8_SB(1, 0), cB + kstep, voffB); PG8_STAGE(PG8_SA(1, 0), cA + kstep, voffA); PG8_STAGE(PG8_SB(1, 1), cB + hstep + kstep, voffB);
;         PG8_WAIT_V(6); PG8_BAR;
.LBB0_1573:
	s_add_u32 s38, s4, 0xe400000
	s_addc_u32 s39, s5, 0
	s_add_u32 s40, s4, 0x10400000
	s_addc_u32 s41, s5, 0
	s_add_u32 s42, s4, 0x12400000
	s_addc_u32 s43, s5, 0
	s_add_u32 s44, s4, 0x14500000
	s_addc_u32 s45, s5, 0
	s_add_u32 s54, s4, 0x16600000
	s_addc_u32 s55, s5, 0
	s_add_u32 s52, s4, 0x16f00000
	s_addc_u32 s53, s5, 0
	s_add_i32 s18, s13, 0x18000
	s_and_b32 s2, s2, 3
	s_add_i32 s63, s18, s3
	s_mov_b64 s[56:57], 0x80
	s_lshl_b32 s31, s15, 6
	s_lshl_b32 s15, s15, 13
	s_lshl_b32 s62, s2, 5
	s_lshl_b32 s2, s2, 12
	v_lshl_add_u64 v[8:9], v[8:9], 0, s[56:57]
	s_mov_b32 m0, s63
	s_add_i32 s64, s63, 0x2000
	s_add_i32 s65, s95, 0x8000
	s_add_i32 s66, s95, 0xa000
	global_load_lds_dwordx4 v[8:9], off
	v_lshl_add_u64 v[6:7], v[6:7], 0, s[56:57]
	s_mov_b32 m0, s64
	s_add_u32 s16, s8, 0x40080
	global_load_lds_dwordx4 v[6:7], off
	v_lshl_add_u64 v[2:3], v[2:3], 0, s[56:57]
	s_mov_b32 m0, s65
	s_addc_u32 s17, s9, 0
	s_add_i32 s19, s13, 0x1c000
	global_load_lds_dwordx4 v[2:3], off
	v_lshl_add_u64 v[2:3], v[4:5], 0, s[56:57]
	s_mov_b32 m0, s66
	s_add_i32 s67, s19, s3
	global_load_lds_dwordx4 v[2:3], off
	v_lshl_add_u64 v[2:3], s[16:17], 0, v[138:139]
	s_mov_b32 m0, s67
	s_add_i32 s26, s67, 0x2000
	global_load_lds_dwordx4 v[2:3], off
	v_lshl_add_u64 v[2:3], s[16:17], 0, v[140:141]
	s_mov_b32 m0, s26
	v_and_b32_e32 v145, 15, v10
	global_load_lds_dwordx4 v[2:3], off
	s_waitcnt vmcnt(8)
	s_barrier
	v_bfe_u32 v2, v10, 4, 2
	v_lshlrev_b32_e32 v3, 4, v2
	v_lshlrev_b32_e32 v4, 2, v10
	v_lshl_or_b32 v3, v145, 6, v3
	v_and_b32_e32 v4, 32, v4
	v_lshlrev_b32_e32 v142, 5, v2
	v_bitop3_b32 v5, v3, s15, v4 bitop3:0xde
	v_bitop3_b32 v4, v3, s2, v4 bitop3:0xde
	v_lshlrev_b32_e32 v144, 2, v2
	v_lshl_add_u64 v[2:3], s[4:5], 0, v[142:143]
	s_mov_b64 s[4:5], 0x500000
	v_lshl_add_u64 v[146:147], v[2:3], 0, s[4:5]
	v_lshlrev_b32_e32 v2, 14, v14
	v_and_b32_e32 v2, 0xffff8000, v2
	v_lshl_add_u32 v2, v15, 11, v2
	v_and_b32_e32 v3, 1, v14
	v_lshl_or_b32 v2, v3, 6, v2
	v_lshl_add_u32 v148, v16, 1, v2
	v_lshlrev_b32_e32 v2, 14, v11
	v_and_b32_e32 v2, 0xffff8000, v2
	s_waitcnt vmcnt(6)
	s_cmpk_lt_u32 s12, 0x100
	v_lshl_add_u32 v2, v12, 11, v2
	v_and_b32_e32 v3, 1, v11
	s_cselect_b64 s[60:61], -1, 0
	s_bitcmp0_b32 s12, 6
	v_lshl_or_b32 v2, v3, 6, v2
	s_cselect_b64 s[2:3], -1, 0
	v_or_b32_e32 v168, 16, v145
	v_or_b32_e32 v169, 32, v145
	v_or_b32_e32 v170, 48, v145
	s_ashr_i32 s27, s69, 31
	s_ashr_i32 s28, s86, 31
	v_mov_b32_e32 v149, v143
	v_lshl_add_u32 v150, v13, 1, v2
	v_mov_b32_e32 v151, v143
	v_mov_b64_e32 v[152:153], 0x4a4
	v_mov_b64_e32 v[154:155], 0x4a3
	v_add_u32_e32 v171, s7, v4
	v_add_u32_e32 v172, s14, v4
	v_add_u32_e32 v173, s13, v5
	v_add_u32_e32 v174, s18, v4
	v_add_u32_e32 v175, s19, v4
	s_mov_b32 s68, 0x3e38aa3b
	s_movk_i32 s29, 0x4200
	s_movk_i32 s46, 0x1fdf
	s_movk_i32 s47, 0x1fef
	s_movk_i32 s36, 0x1fff
	v_mov_b32_e32 v176, 0x1fcf
	v_mov_b32_e32 v177, 0x2100
	s_mov_b32 s37, 0
	s_barrier
	s_branch .LBB0_1576

; #define PG8_STAGE(bufoff, gbase, voff) do { _Pragma("unroll") for (int _i = 0; _i < 2; ++_i) \
;         __builtin_amdgcn_global_load_lds((const unsigned*)((const char*)(gbase) + (voff)[_i]), (PG8_LAS unsigned*)(lds + (bufoff) + ldsw + _i * 8192), 16, 0, 0); } while (0)
; #define PG8_WAIT_V(n) asm volatile("s_waitcnt vmcnt(" #n ")" ::: "memory")
; #define PG8_BAR __builtin_amdgcn_s_barrier()
; template <class Epi, class Sched, bool ALIGN_EPI = false, bool SP2 = false>
; __device__ __forceinline__ void gemm_phase(PG8_LAS unsigned char* lds, const Gemm g, const Sched& S, const Epi& E) {
;     ...
;     if constexpr (SP2) {
;         PG8_STAGE(PG8_SB(0, 0), cB, voffB); PG8_STAGE(PG8_SB(0, 1), cB + hstep, voffB); PG8_STAGE(PG8_SA(0, 0), cA, voffA); PG8_STAGE(PG8_SA(0, 1), cA + hstep, voffA);
;         if (wr == 1) PG8_BAR;
;         PG8_WAIT_V(2); PG8_BAR;
;         PG8_STAGE(PG8_SB(1, 0), cB + kstep, voffB); PG8_STAGE(PG8_SA(1, 0), cA + kstep, voffA); PG8_STAGE(PG8_SB(1, 1), cB + hstep + kstep, voffB);
;         PG8_WAIT_V(6); PG8_BAR;
.LBB0_2124:
	s_add_u32 s6, s2, 0xa200000
	s_addc_u32 s7, s3, 0
	s_lshl_b32 s2, s8, 5
	s_add_i32 s22, s12, 0x18000
	s_and_b32 s20, s2, 0x60
	s_add_i32 s52, s22, s15
	s_mov_b64 s[8:9], 0x80
	s_lshl_b32 s17, s14, 13
	s_lshl_b32 s21, s20, 7
	v_lshl_add_u64 v[8:9], v[8:9], 0, s[8:9]
	s_mov_b32 m0, s52
	s_add_i32 s53, s52, 0x2000
	s_add_i32 s54, s47, 0x8000
	s_add_i32 s55, s47, 0xa000
	global_load_lds_dwordx4 v[8:9], off
	v_lshl_add_u64 v[4:5], v[4:5], 0, s[8:9]
	s_mov_b32 m0, s53
	s_add_u32 s2, s38, 0x40080
	global_load_lds_dwordx4 v[4:5], off
	v_lshl_add_u64 v[2:3], v[2:3], 0, s[8:9]
	s_mov_b32 m0, s54
	s_addc_u32 s3, s39, 0
	s_add_i32 s23, s12, 0x1c000
	global_load_lds_dwordx4 v[2:3], off
	v_lshl_add_u64 v[2:3], v[6:7], 0, s[8:9]
	s_mov_b32 m0, s55
	s_add_i32 s56, s23, s15
	global_load_lds_dwordx4 v[2:3], off
	v_lshl_add_u64 v[2:3], s[2:3], 0, v[132:133]
	s_mov_b32 m0, s56
	s_add_i32 s57, s56, 0x2000
	global_load_lds_dwordx4 v[2:3], off
	v_lshl_add_u64 v[2:3], s[2:3], 0, v[136:137]
	s_mov_b32 m0, s57
	s_cmpk_lt_u32 s11, 0x100
	global_load_lds_dwordx4 v[2:3], off
	s_waitcnt vmcnt(8)
	s_barrier
	v_lshrrev_b32_e32 v3, 1, v10
	v_and_b32_e32 v3, 24, v3
	v_and_b32_e32 v2, 15, v10
	v_lshlrev_b32_e32 v4, 1, v3
	v_lshl_or_b32 v146, s14, 6, v2
	v_lshl_or_b32 v2, v2, 6, v4
	v_lshlrev_b32_e32 v4, 2, v10
	v_or_b32_e32 v147, s20, v3
	v_lshlrev_b32_e32 v3, 14, v14
	v_and_b32_e32 v4, 32, v4
	v_and_b32_e32 v3, 0xffff8000, v3
	v_bitop3_b32 v5, v2, s17, v4 bitop3:0xde
	v_bitop3_b32 v2, v2, s21, v4 bitop3:0xde
	v_lshl_add_u32 v3, v15, 11, v3
	v_and_b32_e32 v4, 1, v14
	v_lshl_or_b32 v3, v4, 6, v3
	v_lshl_add_u32 v138, v16, 1, v3
	v_lshlrev_b32_e32 v3, 14, v11
	v_and_b32_e32 v3, 0xffff8000, v3
	s_waitcnt vmcnt(6)
	v_lshl_add_u32 v3, v12, 11, v3
	v_and_b32_e32 v4, 1, v11
	v_lshl_or_b32 v3, v4, 6, v3
	s_sext_i32_i8 s63, s10
	s_cselect_b64 s[10:11], -1, 0
	s_ashr_i32 s58, s27, 31
	v_mov_b32_e32 v139, v133
	v_lshl_add_u32 v140, v13, 1, v3
	v_mov_b32_e32 v141, v133
	v_mov_b64_e32 v[142:143], 0x200
	v_mov_b64_e32 v[144:145], 0x1ff
	v_add_u32_e32 v148, s13, v2
	v_add_u32_e32 v149, s16, v2
	v_add_u32_e32 v150, s12, v5
	v_add_u32_e32 v151, s22, v2
	v_add_u32_e32 v152, s23, v2
	s_mov_b32 s59, 0x40000
	s_mov_b64 s[12:13], 0x48000
	s_mov_b32 s60, 0x48000
	s_mov_b64 s[14:15], 0x50000
	s_mov_b32 s61, 0x50000
	s_mov_b64 s[16:17], 0x58000
	s_mov_b32 s62, 0x58000
	s_barrier
	s_branch .LBB0_2127

; #define PG8_STAGE(bufoff, gbase, voff) do { _Pragma("unroll") for (int _i = 0; _i < 2; ++_i) \
;         __builtin_amdgcn_global_load_lds((const unsigned*)((const char*)(gbase) + (voff)[_i]), (PG8_LAS unsigned*)(lds + (bufoff) + ldsw + _i * 8192), 16, 0, 0); } while (0)
; #define PG8_WAIT_V(n) asm volatile("s_waitcnt vmcnt(" #n ")" ::: "memory")
; #define PG8_BAR __builtin_amdgcn_s_barrier()
; template <class Epi, class Sched, bool ALIGN_EPI = false, bool SP2 = false>
; __device__ __forceinline__ void gemm_phase(PG8_LAS unsigned char* lds, const Gemm g, const Sched& S, const Epi& E) {
;     ...
;     if constexpr (SP2) {
;         PG8_STAGE(PG8_SB(0, 0), cB, voffB); PG8_STAGE(PG8_SB(0, 1), cB + hstep, voffB); PG8_STAGE(PG8_SA(0, 0), cA, voffA); PG8_STAGE(PG8_SA(0, 1), cA + hstep, voffA);
;         if (wr == 1) PG8_BAR;
;         PG8_WAIT_V(2); PG8_BAR;
;         PG8_STAGE(PG8_SB(1, 0), cB + kstep, voffB); PG8_STAGE(PG8_SA(1, 0), cA + kstep, voffA); PG8_STAGE(PG8_SB(1, 1), cB + hstep + kstep, voffB);
;         PG8_WAIT_V(6); PG8_BAR;
.LBB0_2279:
	s_add_u32 s4, s2, 0xe400000
	s_addc_u32 s5, s3, 0
	s_lshl_b32 s2, s6, 5
	s_add_i32 s24, s10, 0x18000
	s_and_b32 s16, s2, 0x60
	s_add_i32 s45, s24, s12
	s_mov_b64 s[6:7], 0x80
	s_lshl_b32 s15, s11, 13
	s_lshl_b32 s17, s16, 7
	v_lshl_add_u64 v[8:9], v[8:9], 0, s[6:7]
	s_mov_b32 m0, s45
	s_add_i32 s46, s45, 0x2000
	s_add_i32 s47, s41, 0x8000
	s_add_i32 s48, s41, 0xa000
	global_load_lds_dwordx4 v[8:9], off
	v_lshl_add_u64 v[6:7], v[6:7], 0, s[6:7]
	s_mov_b32 m0, s46
	s_add_u32 s2, s20, 0x40080
	global_load_lds_dwordx4 v[6:7], off
	v_lshl_add_u64 v[2:3], v[2:3], 0, s[6:7]
	s_mov_b32 m0, s47
	s_addc_u32 s3, s21, 0
	s_add_i32 s25, s10, 0x1c000
	global_load_lds_dwordx4 v[2:3], off
	v_lshl_add_u64 v[2:3], v[4:5], 0, s[6:7]
	s_mov_b32 m0, s48
	s_add_i32 s49, s25, s12
	global_load_lds_dwordx4 v[2:3], off
	v_lshl_add_u64 v[2:3], s[2:3], 0, v[134:135]
	s_mov_b32 m0, s49
	s_add_i32 s52, s49, 0x2000
	global_load_lds_dwordx4 v[2:3], off
	v_lshl_add_u64 v[2:3], s[2:3], 0, v[130:131]
	s_mov_b32 m0, s52
	s_cmpk_lt_u32 s9, 0x100
	global_load_lds_dwordx4 v[2:3], off
	s_waitcnt vmcnt(8)
	s_barrier
	v_lshrrev_b32_e32 v3, 1, v10
	v_and_b32_e32 v3, 24, v3
	v_and_b32_e32 v2, 15, v10
	v_lshlrev_b32_e32 v4, 1, v3
	v_lshl_or_b32 v150, s11, 6, v2
	v_lshl_or_b32 v2, v2, 6, v4
	v_lshlrev_b32_e32 v4, 2, v10
	v_or_b32_e32 v151, s16, v3
	v_lshlrev_b32_e32 v3, 14, v11
	v_and_b32_e32 v4, 32, v4
	v_and_b32_e32 v3, 0xffff8000, v3
	v_bitop3_b32 v5, v2, s15, v4 bitop3:0xde
	v_bitop3_b32 v2, v2, s17, v4 bitop3:0xde
	v_lshl_add_u32 v3, v12, 11, v3
	v_and_b32_e32 v4, 1, v11
	v_lshl_or_b32 v3, v4, 6, v3
	v_lshl_add_u32 v138, v13, 1, v3
	v_lshlrev_b32_e32 v3, 14, v15
	v_and_b32_e32 v3, 0xffff8000, v3
	s_waitcnt vmcnt(6)
	v_lshl_add_u32 v3, v14, 11, v3
	v_and_b32_e32 v4, 1, v15
	v_lshl_or_b32 v3, v4, 6, v3
	s_sext_i32_i16 s33, s8
	s_cselect_b64 s[8:9], -1, 0
	s_ashr_i32 s53, s27, 31
	v_mov_b32_e32 v139, v135
	v_lshl_add_u32 v140, v16, 1, v3
	v_mov_b32_e32 v141, v135
	s_mov_b32 s56, 0
	v_mov_b64_e32 v[142:143], 0xb00
	v_mov_b64_e32 v[144:145], 0xaff
	v_add_u32_e32 v152, s13, v2
	v_add_u32_e32 v153, s14, v2
	v_add_u32_e32 v154, s10, v5
	v_add_u32_e32 v155, s24, v2
	v_add_u32_e32 v156, s25, v2
	s_movk_i32 s57, 0x1600
	s_barrier
	s_branch .LBB0_2282

; #define PG8_STAGE(bufoff, gbase, voff) do { _Pragma("unroll") for (int _i = 0; _i < 2; ++_i) \
;         __builtin_amdgcn_global_load_lds((const unsigned*)((const char*)(gbase) + (voff)[_i]), (PG8_LAS unsigned*)(lds + (bufoff) + ldsw + _i * 8192), 16, 0, 0); } while (0)
; #define PG8_WAIT_V(n) asm volatile("s_waitcnt vmcnt(" #n ")" ::: "memory")
; #define PG8_BAR __builtin_amdgcn_s_barrier()
; template <class Epi, class Sched, bool ALIGN_EPI = false, bool SP2 = false>
; __device__ __forceinline__ void gemm_phase(PG8_LAS unsigned char* lds, const Gemm g, const Sched& S, const Epi& E) {
;     ...
;     if constexpr (SP2) {
;         PG8_STAGE(PG8_SB(0, 0), cB, voffB); PG8_STAGE(PG8_SB(0, 1), cB + hstep, voffB); PG8_STAGE(PG8_SA(0, 0), cA, voffA); PG8_STAGE(PG8_SA(0, 1), cA + hstep, voffA);
;         if (wr == 1) PG8_BAR;
;         PG8_WAIT_V(2); PG8_BAR;
;         PG8_STAGE(PG8_SB(1, 0), cB + kstep, voffB); PG8_STAGE(PG8_SA(1, 0), cA + kstep, voffA); PG8_STAGE(PG8_SB(1, 1), cB + hstep + kstep, voffB);
;         PG8_WAIT_V(6); PG8_BAR;
.LBB0_2353:
	s_add_u32 s6, s2, 0xa200000
	s_addc_u32 s7, s3, 0
	s_lshl_b32 s2, s8, 5
	s_add_i32 s19, s5, 0x18000
	s_and_b32 s17, s2, 0x60
	s_add_i32 s49, s19, s11
	s_mov_b64 s[8:9], 0x80
	s_lshl_b32 s16, s10, 13
	s_lshl_b32 s18, s17, 7
	v_lshl_add_u64 v[8:9], v[8:9], 0, s[8:9]
	s_mov_b32 m0, s49
	s_add_i32 s50, s49, 0x2000
	s_add_i32 s51, s44, 0x8000
	s_add_i32 s52, s44, 0xa000
	global_load_lds_dwordx4 v[8:9], off
	v_lshl_add_u64 v[6:7], v[6:7], 0, s[8:9]
	s_mov_b32 m0, s50
	s_add_u32 s2, s24, 0xb0080
	global_load_lds_dwordx4 v[6:7], off
	v_lshl_add_u64 v[2:3], v[2:3], 0, s[8:9]
	s_mov_b32 m0, s51
	s_addc_u32 s3, s25, 0
	s_add_i32 s20, s5, 0x1c000
	global_load_lds_dwordx4 v[2:3], off
	v_lshl_add_u64 v[2:3], v[4:5], 0, s[8:9]
	s_mov_b32 m0, s52
	s_add_i32 s53, s20, s11
	global_load_lds_dwordx4 v[2:3], off
	v_lshl_add_u64 v[2:3], s[2:3], 0, v[132:133]
	s_mov_b32 m0, s53
	s_add_i32 s54, s53, 0x2000
	global_load_lds_dwordx4 v[2:3], off
	v_lshl_add_u64 v[2:3], s[2:3], 0, v[136:137]
	s_mov_b32 m0, s54
	s_cmpk_lt_u32 s4, 0x100
	global_load_lds_dwordx4 v[2:3], off
	s_waitcnt vmcnt(8)
	s_barrier
	v_lshrrev_b32_e32 v3, 1, v10
	v_and_b32_e32 v3, 24, v3
	v_and_b32_e32 v2, 15, v10
	v_lshlrev_b32_e32 v4, 1, v3
	v_lshl_or_b32 v146, s10, 6, v2
	v_lshl_or_b32 v2, v2, 6, v4
	v_lshlrev_b32_e32 v4, 2, v10
	v_and_b32_e32 v4, 32, v4
	v_bitop3_b32 v5, v2, s16, v4 bitop3:0xde
	v_bitop3_b32 v4, v2, s18, v4 bitop3:0xde
	v_or_b32_e32 v147, s17, v3
	v_lshrrev_b32_e32 v3, 1, v15
	v_mul_lo_u32 v2, v17, s12
	s_mov_b32 s4, 0xb000
	v_mad_u64_u32 v[2:3], s[16:17], v3, s4, v[2:3]
	v_or_b32_e32 v2, v2, v16
	s_mov_b64 s[2:3], 0xb0080
	v_add_lshl_u32 v2, v2, v18, 1
	v_mov_b32_e32 v3, v133
	v_lshl_add_u64 v[138:139], v[2:3], 0, s[2:3]
	v_lshrrev_b32_e32 v3, 1, v11
	v_mul_lo_u32 v2, v12, s12
	v_mad_u64_u32 v[2:3], s[16:17], v3, s4, v[2:3]
	s_waitcnt vmcnt(6)
	v_or_b32_e32 v2, v2, v13
	v_add_lshl_u32 v2, v2, v14, 1
	v_mov_b32_e32 v3, v133
	s_sext_i32_i8 s63, s15
	s_cselect_b64 s[10:11], -1, 0
	s_ashr_i32 s55, s27, 31
	v_lshl_add_u64 v[140:141], v[2:3], 0, s[2:3]
	v_mov_b64_e32 v[142:143], 0x200
	v_mov_b64_e32 v[144:145], 0x1ff
	v_add_u32_e32 v148, s13, v4
	v_add_u32_e32 v149, s14, v4
	v_add_u32_e32 v150, s5, v5
	v_add_u32_e32 v151, s19, v4
	v_add_u32_e32 v152, s20, v4
	s_mov_b64 s[12:13], 0x40000
	s_mov_b32 s56, 0x40000
	s_mov_b64 s[14:15], 0x48000
	s_mov_b32 s57, 0x48000
	s_mov_b64 s[16:17], 0x50000
	s_mov_b32 s58, 0x50000
	s_mov_b64 s[18:19], 0x58000
	s_mov_b32 s59, 0x58000
	s_barrier
	s_branch .LBB0_2356
